# adds: NA tile loop persistent bf16-ones operand for the row-sum MFMAs; diff loop static priority for waves 4-7
# baseline (speedup 1.0000x reference)
.Lf_462:
	s_and_b32 s17, s19, 0x18000
	v_add_u32_e32 v0, s17, v227
	v_add_u32_e32 v2, v0, v228
	ds_read_b128 v[96:99], v2
	ds_read_b128 v[100:103], v2 offset:4096
	v_add_u32_e32 v2, v0, v226
	ds_read_b128 v[180:183], v2
	ds_read_b128 v[230:233], v2 offset:4096
	v_add_u32_e32 v2, v0, v225
	v_add_u32_e32 v0, v0, v224
	s_min_u32 s16, s28, 1
	ds_read_b128 v[234:237], v2
	ds_read_b128 v[238:241], v2 offset:4096
	ds_read_b128 v[242:245], v0
	ds_read_b128 v[246:249], v0 offset:4096
	s_lshl_b32 s16, s16, 15
	s_sub_i32 s16, s19, s16
	s_and_b32 s16, s16, 0x18000
	v_add_u32_e32 v0, s16, v195
	s_waitcnt lgkmcnt(6)
	v_mfma_f32_32x32x16_bf16 v[112:127], v[96:99], v[156:159], 0
	s_add_i32 s22, s13, 1
	s_add_i32 s61, s19, 0x8000
	s_add_i32 s20, s61, 0x10000
	s_and_b32 s20, s20, 0x18000
	v_mfma_f32_32x32x16_bf16 v[96:111], v[100:103], v[156:159], 0
	s_add_i32 s20, s20, s23
	s_add_i32 s62, s22, -2
	s_cmpk_gt_u32 s62, 0x41
	s_cselect_b32 s61, 1, 0
	s_waitcnt lgkmcnt(4)
	v_mfma_f32_32x32x16_bf16 v[112:127], v[180:183], v[152:155], v[112:127]
	s_cmp_lt_u32 s62, 62
	s_cselect_b32 s16, 0, 0xffffffc0
	s_cselect_b32 s17, s9, s10
	s_add_i32 s16, s16, s22
	v_mfma_f32_32x32x16_bf16 v[96:111], v[230:233], v[152:155], v[96:111]
	s_lshl_b32 s16, s16, 6
	s_add_i32 s62, s16, s17
	s_ashr_i32 s63, s62, 31
	s_add_u32 s30, s62, s11
	s_waitcnt lgkmcnt(2)
	v_mfma_f32_32x32x16_bf16 v[112:127], v[234:237], v[148:151], v[112:127]
	s_addc_u32 s31, s63, 0
	s_lshl_b64 s[30:31], s[30:31], 7
	s_add_u32 s34, s95, s30
	s_addc_u32 s35, s3, s31
	v_mfma_f32_32x32x16_bf16 v[96:111], v[238:241], v[148:151], v[96:111]
	s_add_u32 s16, s62, s12
	s_addc_u32 s17, s63, 0
	s_lshl_b64 s[16:17], s[16:17], 7
	s_add_u32 s16, s95, s16
	s_waitcnt lgkmcnt(0)
	v_mfma_f32_32x32x16_bf16 v[112:127], v[242:245], v[144:147], v[112:127]
	s_addc_u32 s17, s3, s17
	s_add_u32 s30, s14, s30
	s_addc_u32 s31, s15, s31
	v_mfma_f32_32x32x16_bf16 v[96:111], v[246:249], v[144:147], v[96:111]
	ds_read_b64_tr_b16 v[176:177], v0 offset:16384
	ds_read_b64_tr_b16 v[178:179], v0 offset:16896
	ds_read_b64_tr_b16 v[172:173], v0 offset:17408
	ds_read_b64_tr_b16 v[174:175], v0 offset:17920
	ds_read_b64_tr_b16 v[168:169], v0 offset:18432
	ds_read_b64_tr_b16 v[170:171], v0 offset:18944
	ds_read_b64_tr_b16 v[164:165], v0 offset:19456
	ds_read_b64_tr_b16 v[166:167], v0 offset:19968
	ds_read_b64_tr_b16 v[160:161], v0 offset:20480
	ds_read_b64_tr_b16 v[162:163], v0 offset:20992
	ds_read_b64_tr_b16 v[10:11], v0 offset:21504
	ds_read_b64_tr_b16 v[12:13], v0 offset:22016
	ds_read_b64_tr_b16 v[6:7], v0 offset:22528
	ds_read_b64_tr_b16 v[8:9], v0 offset:23040
	ds_read_b64_tr_b16 v[2:3], v0 offset:23552
	ds_read_b64_tr_b16 v[4:5], v0 offset:24064
	v_max3_f32 v14, v112, v113, v114
	v_max3_f32 v15, v115, v116, v117
	v_max3_f32 v180, v118, v119, v120
	v_max3_f32 v181, v121, v122, v123
	v_max3_f32 v182, v124, v125, v126
	v_max3_f32 v183, v96, v97, v98
	v_max3_f32 v230, v99, v100, v101
	v_max3_f32 v231, v102, v103, v104
	s_nop 0
	v_max3_f32 v14, v14, v15, v180
	v_max3_f32 v232, v105, v106, v107
	v_max3_f32 v15, v181, v182, v127
	v_max3_f32 v233, v108, v109, v110
	v_max3_f32 v180, v183, v230, v231
	v_max3_f32 v181, v232, v233, v111
	s_nop 0
	v_max3_f32 v14, v14, v15, v180
	v_max_f32_e32 v14, v14, v181
	v_mov_b32_e32 v15, v14
	s_nop 1
	v_permlane32_swap_b32_e32 v15, v14
	v_max_f32_e32 v14, v14, v15
	v_cmp_lt_f32_e32 vcc, 0x42800000, v14
	s_waitcnt lgkmcnt(0)
	s_cbranch_vccz .Lf_459
	s_branch .Lf_to463
	.p2align 6

.LBB0_527:
	v_and_b32_e32 v0, 0xc0, v6
	v_lshlrev_b32_e32 v4, 5, v4
	v_readlane_b32 s0, v254, 6
	v_and_b32_e32 v4, 32, v4
	v_lshl_or_b32 v0, v2, 8, v0
	s_add_i32 s0, s10, s0
	v_or3_b32 v238, v0, v4, v5
	v_or_b32_e32 v0, s0, v7
	v_add_u32_e32 v0, -4, v0
	v_sub_co_u32_e64 v4, s[8:9], s0, 4
	v_min_u32_e32 v0, 56, v0
	v_readfirstlane_b32 s1, v4
	v_cndmask_b32_e64 v239, v0, 0, s[8:9]
	s_min_u32 s68, s1, 56
	v_sub_co_u32_e64 v0, s[0:1], s0, 3
	s_nop 0
	v_readfirstlane_b32 s13, v0
	v_lshrrev_b32_e32 v0, 1, v3
	s_min_u32 s13, s13, 56
	v_bfe_u32 v3, v3, 1, 3
	v_add_u16_e32 v4, s12, v8
	v_bitop3_b32 v0, v2, v0, 7 bitop3:0x78
	s_add_i32 s69, s34, 4
	v_lshrrev_b16_e32 v4, 1, v4
	s_add_i32 s13, s13, 7
	v_lshlrev_b32_e32 v241, 4, v0
	v_or_b32_e32 v0, 2, v2
	v_bitop3_b32 v5, v2, v3, 2 bitop3:0x36
	s_and_b64 s[0:1], s[0:1], exec
	v_lshlrev_b32_e32 v242, 4, v5
	v_or_b32_e32 v5, 4, v2
	v_bitop3_b32 v6, v2, v3, 4 bitop3:0x36
	v_bitop3_b32 v0, v4, v0, 7 bitop3:0x6c
	v_lshlrev_b32_e32 v243, 4, v6
	v_or_b32_e32 v6, 6, v2
	v_lshlrev_b32_e32 v246, 4, v0
	v_bitop3_b32 v0, v4, v5, 7 bitop3:0x6c
	v_readlane_b32 s0, v254, 34
	s_cselect_b32 s74, 7, s13
	v_lshlrev_b32_e32 v247, 4, v0
	v_bitop3_b32 v0, v4, v6, 7 bitop3:0x6c
	s_add_i32 s0, s0, s31
	v_bitop3_b32 v3, v2, v3, 6 bitop3:0x36
	v_bitop3_b32 v2, v4, v2, 7 bitop3:0x6c
	v_lshlrev_b32_e32 v248, 4, v0
	v_sub_u32_e32 v0, s0, v7
	v_mov_b32_e32 v14, v1
	v_mov_b32_e32 v15, v1
	v_add_lshl_u32 v237, s12, v8, 7
	v_add_u32_e32 v210, 0, v9
	v_lshlrev_b32_e32 v244, 4, v3
	v_lshlrev_b32_e32 v245, 4, v2
	s_sub_i32 s86, s31, s11
	v_subrev_u32_e32 v249, s10, v0
	v_mov_b32_e32 v0, v1
	v_mov_b32_e32 v2, v1
	v_mov_b32_e32 v3, v1
	v_mov_b32_e32 v4, v1
	v_mov_b32_e32 v5, v1
	v_mov_b32_e32 v6, v1
	v_mov_b32_e32 v7, v1
	v_mov_b32_e32 v8, v1
	v_mov_b32_e32 v9, v1
	v_mov_b32_e32 v10, v1
	v_mov_b32_e32 v11, v1
	v_mov_b32_e32 v12, v1
	v_mov_b32_e32 v13, v1
	v_mov_b64_e32 v[30:31], v[14:15]
	v_mov_b64_e32 v[46:47], v[14:15]
	v_mov_b64_e32 v[62:63], v[14:15]
	v_mov_b64_e32 v[78:79], v[14:15]
	s_movk_i32 s50, 0xc0
	s_mov_b32 s51, 0
	s_lshl_b32 s75, s12, 6
	v_add_u32_e32 v240, 7, v239
	s_mov_b32 s83, 2
	s_add_i32 s86, s86, -4
	s_mov_b64 s[46:47], 0
	v_mov_b32_e32 v212, 0
	v_mov_b64_e32 v[28:29], v[12:13]
	v_mov_b64_e32 v[26:27], v[10:11]
	v_mov_b64_e32 v[24:25], v[8:9]
	v_mov_b64_e32 v[22:23], v[6:7]
	v_mov_b64_e32 v[20:21], v[4:5]
	v_mov_b64_e32 v[18:19], v[2:3]
	v_mov_b64_e32 v[16:17], v[0:1]
	v_mov_b64_e32 v[44:45], v[12:13]
	v_mov_b64_e32 v[42:43], v[10:11]
	v_mov_b64_e32 v[40:41], v[8:9]
	v_mov_b64_e32 v[38:39], v[6:7]
	v_mov_b64_e32 v[36:37], v[4:5]
	v_mov_b64_e32 v[34:35], v[2:3]
	v_mov_b64_e32 v[32:33], v[0:1]
	v_mov_b64_e32 v[60:61], v[12:13]
	v_mov_b64_e32 v[58:59], v[10:11]
	v_mov_b64_e32 v[56:57], v[8:9]
	v_mov_b64_e32 v[54:55], v[6:7]
	v_mov_b64_e32 v[52:53], v[4:5]
	v_mov_b64_e32 v[50:51], v[2:3]
	v_mov_b64_e32 v[48:49], v[0:1]
	v_mov_b64_e32 v[76:77], v[12:13]
	v_mov_b64_e32 v[74:75], v[10:11]
	v_mov_b64_e32 v[72:73], v[8:9]
	v_mov_b64_e32 v[70:71], v[6:7]
	v_mov_b64_e32 v[68:69], v[4:5]
	v_mov_b64_e32 v[66:67], v[2:3]
	v_mov_b64_e32 v[64:65], v[0:1]
	v_mov_b32_e32 v116, s60
	v_mov_b32_e32 v117, s60
	v_mov_b32_e32 v118, s60
	v_mov_b32_e32 v119, s60

.Lna_547:
	v_exp_f32_e32 v15, v144
	v_exp_f32_e32 v144, v128
	v_exp_f32_e32 v128, v145
	v_exp_f32_e32 v129, v129
	v_exp_f32_e32 v145, v146
	v_exp_f32_e32 v130, v130
	v_exp_f32_e32 v146, v147
	v_exp_f32_e32 v131, v131
	v_exp_f32_e32 v147, v148
	v_exp_f32_e32 v148, v132
	v_exp_f32_e32 v149, v149
	v_exp_f32_e32 v218, v133
	v_exp_f32_e32 v150, v150
	v_exp_f32_e32 v219, v134
	v_exp_f32_e32 v151, v151
	v_exp_f32_e32 v220, v135
	v_exp_f32_e32 v132, v152
	v_exp_f32_e32 v133, v136
	v_exp_f32_e32 v134, v153
	v_exp_f32_e32 v135, v137
	v_exp_f32_e32 v137, v154
	v_exp_f32_e32 v138, v138
	v_exp_f32_e32 v152, v155
	v_exp_f32_e32 v139, v139
	v_exp_f32_e32 v153, v156
	v_exp_f32_e32 v154, v140
	v_exp_f32_e32 v155, v157
	v_exp_f32_e32 v156, v141
	v_exp_f32_e32 v157, v158
	v_exp_f32_e32 v158, v142
	v_exp_f32_e32 v159, v159
	v_exp_f32_e32 v143, v143
	v_cvt_pk_bf16_f32 v128, v15, v128
	v_cvt_pk_bf16_f32 v132, v132, v134
	v_cvt_pk_bf16_f32 v136, v144, v129
	v_cvt_pk_bf16_f32 v140, v133, v135
	v_cvt_pk_bf16_f32 v129, v145, v146
	v_cvt_pk_bf16_f32 v133, v137, v152
	v_cvt_pk_bf16_f32 v137, v130, v131
	v_cvt_pk_bf16_f32 v141, v138, v139
	v_cvt_pk_bf16_f32 v130, v147, v149
	v_cvt_pk_bf16_f32 v134, v153, v155
	v_cvt_pk_bf16_f32 v138, v148, v218
	v_cvt_pk_bf16_f32 v142, v154, v156
	v_cvt_pk_bf16_f32 v131, v150, v151
	v_cvt_pk_bf16_f32 v135, v157, v159
	v_cvt_pk_bf16_f32 v139, v219, v220
	v_cvt_pk_bf16_f32 v143, v158, v143
	ds_read_b64_tr_b16 v[144:145], v0 offset:12288
	ds_read_b64_tr_b16 v[146:147], v0 offset:12800
	ds_read_b64_tr_b16 v[148:149], v0 offset:13312
	ds_read_b64_tr_b16 v[150:151], v0 offset:13824
	ds_read_b64_tr_b16 v[152:153], v0 offset:14336
	ds_read_b64_tr_b16 v[154:155], v0 offset:14848
	ds_read_b64_tr_b16 v[156:157], v0 offset:15360
	ds_read_b64_tr_b16 v[158:159], v0 offset:15872
	s_setprio 1
	s_waitcnt lgkmcnt(8)
	v_mfma_f32_32x32x16_bf16 v[16:31], v[192:195], v[128:131], v[16:31]
	v_mfma_f32_32x32x16_bf16 v[16:31], v[10:13], v[132:135], v[16:31]
	v_mfma_f32_32x32x16_bf16 v[16:31], v[6:9], v[136:139], v[16:31]
	v_mfma_f32_32x32x16_bf16 v[16:31], v[2:5], v[140:143], v[16:31]
	s_waitcnt lgkmcnt(6)
	v_mfma_f32_32x32x16_bf16 v[32:47], v[144:147], v[128:131], v[32:47]
	v_mfma_f32_32x32x16_bf16 v[48:63], v[116:119], v[128:131], v[48:63]
	s_waitcnt lgkmcnt(4)
	v_mfma_f32_32x32x16_bf16 v[32:47], v[148:151], v[132:135], v[32:47]
	v_mfma_f32_32x32x16_bf16 v[48:63], v[116:119], v[132:135], v[48:63]
	s_waitcnt lgkmcnt(2)
	v_mfma_f32_32x32x16_bf16 v[32:47], v[152:155], v[136:139], v[32:47]
	v_mfma_f32_32x32x16_bf16 v[48:63], v[116:119], v[136:139], v[48:63]
	s_waitcnt lgkmcnt(0)
	v_mfma_f32_32x32x16_bf16 v[32:47], v[156:159], v[140:143], v[32:47]
	v_mfma_f32_32x32x16_bf16 v[48:63], v[116:119], v[140:143], v[48:63]
	s_setprio 0
	s_branch .Lna_next

.Lna_541:
	v_exp_f32_e32 v0, v14
	v_exp_f32_e32 v14, v15
	v_exp_f32_e32 v15, v80
	v_exp_f32_e32 v81, v81
	v_exp_f32_e32 v82, v82
	v_exp_f32_e32 v83, v83
	v_exp_f32_e32 v94, v84
	v_exp_f32_e32 v95, v85
	v_exp_f32_e32 v84, v86
	v_exp_f32_e32 v85, v87
	v_exp_f32_e32 v86, v88
	v_exp_f32_e32 v87, v89
	v_exp_f32_e32 v88, v90
	v_exp_f32_e32 v89, v91
	v_exp_f32_e32 v90, v92
	v_exp_f32_e32 v91, v93
	v_cvt_pk_bf16_f32 v80, v0, v14
	v_cvt_pk_bf16_f32 v84, v84, v85
	v_cvt_pk_bf16_f32 v81, v15, v81
	v_cvt_pk_bf16_f32 v85, v86, v87
	v_cvt_pk_bf16_f32 v82, v82, v83
	v_cvt_pk_bf16_f32 v86, v88, v89
	v_cvt_pk_bf16_f32 v83, v94, v95
	v_cvt_pk_bf16_f32 v87, v90, v91
	s_setprio 1
	s_waitcnt lgkmcnt(0)
	v_mfma_f32_32x32x16_bf16 v[32:47], v[10:13], v[80:83], v[32:47]
	v_mfma_f32_32x32x16_bf16 v[32:47], v[6:9], v[84:87], v[32:47]
	v_mfma_f32_32x32x16_bf16 v[16:31], v[96:99], v[80:83], v[16:31]
	v_mfma_f32_32x32x16_bf16 v[48:63], v[116:119], v[80:83], v[48:63]
	v_mfma_f32_32x32x16_bf16 v[48:63], v[116:119], v[84:87], v[48:63]
	v_mfma_f32_32x32x16_bf16 v[16:31], v[2:5], v[84:87], v[16:31]
	s_setprio 0
